# attention: first 8 K-fragment LDS reads issued right after the step barrier, ahead of the commit writes and global prefetch loads (run 1)
# baseline (speedup 1.0000x reference)
; #define LAS __attribute__((address_space(3)))
; DI void attn_tile(bool MASK, const LAS unsigned char* Ks, const LAS unsigned char* Vs, const bf16x8 (&qr)[6], f32x16& negm, float& mrun, float& lrun, f32x16& o0, f32x16& o1,
;                                        int kv0, int qrow, int r32, int hi) {
;     f32x16 p0, p1;
;     __builtin_amdgcn_s_setprio(1);
;     {
;         const bf16x8 a0 = *(const LAS bf16x8*)(Ks + r32 * 208 + hi * 16);
;         const bf16x8 a1 = *(const LAS bf16x8*)(Ks + (32 + r32) * 208 + hi * 16);
;         p0 = MFMA32(a0, qr[0], negm); p1 = MFMA32(a1, qr[0], negm);
;     }
; #pragma unroll
;     for (int d0 = 1; d0 < 6; ++d0) {
;         const bf16x8 a0 = *(const LAS bf16x8*)(Ks + r32 * 208 + (2 * d0 + hi) * 16);
;         const bf16x8 a1 = *(const LAS bf16x8*)(Ks + (32 + r32) * 208 + (2 * d0 + hi) * 16);
;         p0 = MFMA32(a0, qr[d0], p0); p1 = MFMA32(a1, qr[d0], p1);
;     }
;     __builtin_amdgcn_s_setprio(0);
;     if (MASK) {
;         asm volatile("" ::: "memory");
; #pragma unroll
;         for (int r = 0; r < 16; ++r) { const int kv = kv0 + crow(r, hi); if (kv > qrow) p0[r] = -INFINITY; if (kv + 32 > qrow) p1[r] = -INFINITY; }
;     }
;     float mxa = max3f(p0[0], p0[1], p1[0]), mxb = max3f(p0[2], p0[3], p1[1]); mxa = max3f(mxa, p1[2], p1[3]);
; #pragma unroll
;     for (int r = 4; r < 16; r += 4) { mxa = max3f(mxa, p0[r], p0[r + 1]); mxb = max3f(mxb, p0[r + 2], p0[r + 3]); mxa = max3f(mxa, p1[r], p1[r + 1]); mxb = max3f(mxb, p1[r + 2], p1[r + 3]); }
;     float mx = max2f(mxa, mxb);
;     mx = max2f(mx, __shfl_xor(mx, 32));
;     if (__any(mx > AT_THR)) {
;         const float dm = max2f(mx, 0.f);
;         const float alpha = __builtin_amdgcn_exp2f(-dm);
;         mrun += dm; lrun *= alpha;
; #pragma unroll
;         for (int r = 0; r < 16; ++r) { o0[r] *= alpha; o1[r] *= alpha; p0[r] -= dm; p1[r] -= dm; negm[r] = -mrun; }
;     }
;     float ls = 0.f;
; #pragma unroll
;     for (int r = 0; r < 16; ++r) { p0[r] = __builtin_amdgcn_exp2f(p0[r]); p1[r] = __builtin_amdgcn_exp2f(p1[r]); ls += p0[r] + p1[r]; }
;     lrun += ls;
; DI void attn_unit(int b, int h, int qb, const bf16* Qb, const bf16* Kb, const bf16* Vt, const int* positions, bf16* O, LAS unsigned char* lds, int tid) {
;     ...
;     for (int t = 0; t < NT; t += 3) {
;         __syncthreads();
;         AT_COMMIT(B, 1); AT_ISSUE(B, t + 4);
;         AT_TILE(t, 0);
.LBB0_849:
	s_add_i32 s33, s23, 4
	s_min_i32 s33, s33, s20
	v_mad_i64_i32 v[246:247], s[34:35], s33, v161, v[190:191]
	v_mad_i64_i32 v[248:249], s[34:35], s33, v161, v[194:195]
	v_add3_u32 v0, v204, v199, s29
	s_lshl_b32 s34, s33, 6
	s_waitcnt lgkmcnt(0)
	s_barrier
	s_cmp_gt_i32 s21, s22
	s_cbranch_scc1 .Lkf_skip0
	v_add_u32_e32 v3, v206, v160
	ds_read_b128 v[4:7], v3
	ds_read_b128 v[8:11], v3 offset:32
	ds_read_b128 v[12:15], v3 offset:64
	ds_read_b128 v[214:217], v3 offset:96
	ds_read_b128 v[218:221], v3 offset:128
	ds_read_b128 v[222:225], v3 offset:160
	ds_read_b128 v[226:229], v3 offset:6656
	ds_read_b128 v[230:233], v3 offset:6688
	s_waitcnt vmcnt(3)
	ds_write_b128 v209, v[130:133] offset:22016
	ds_write_b128 v210, v[106:109] offset:22016
	ds_write2_b64 v0, v[110:111], v[112:113] offset1:1
	s_ashr_i32 s35, s34, 31
	global_load_dwordx4 v[130:133], v[246:247], off
	global_load_dwordx4 v[106:109], v[248:249], off
	v_lshl_add_u64 v[246:247], s[34:35], 1, v[192:193]
	global_load_dwordx4 v[110:113], v[246:247], off
	s_cmp_lt_i32 s23, s12
	s_setprio 1
	s_waitcnt lgkmcnt(10)
	v_mfma_f32_32x32x16_bf16 v[82:97], v[4:7], v[154:157], v[50:65]
	ds_read_b128 v[234:237], v3 offset:6720
	s_waitcnt lgkmcnt(10)
	v_mfma_f32_32x32x16_bf16 v[82:97], v[8:11], v[150:153], v[82:97]
	ds_read_b128 v[238:241], v3 offset:6752
	s_waitcnt lgkmcnt(10)
	v_mfma_f32_32x32x16_bf16 v[82:97], v[12:15], v[146:149], v[82:97]
	ds_read_b128 v[242:245], v3 offset:6784
	s_waitcnt lgkmcnt(10)
	v_mfma_f32_32x32x16_bf16 v[82:97], v[214:217], v[126:129], v[82:97]
	ds_read_b128 v[246:249], v3 offset:6816
	s_waitcnt lgkmcnt(10)
	v_mfma_f32_32x32x16_bf16 v[82:97], v[218:221], v[122:125], v[82:97]
	s_waitcnt lgkmcnt(9)
	v_mfma_f32_32x32x16_bf16 v[82:97], v[222:225], v[118:121], v[82:97]
	s_cbranch_scc0 .Lat_m0
	s_setprio 0
	v_add_u32_e32 v3, v205, v208
	v_add_u32_e32 v0, 0x4000, v3
	v_add_u32_e32 v3, 0x3000, v3
	s_waitcnt lgkmcnt(8)
	v_mfma_f32_32x32x16_bf16 v[66:81], v[226:229], v[154:157], v[50:65]
	ds_read2_b64 v[226:229], v3 offset0:128 offset1:130
	s_waitcnt lgkmcnt(8)
	v_mfma_f32_32x32x16_bf16 v[66:81], v[230:233], v[150:153], v[66:81]
	ds_read2_b64 v[230:233], v0 offset0:160 offset1:162
	s_nop 3
	v_exp_f32_e32 v214, v82
	v_exp_f32_e32 v215, v83
	v_exp_f32_e32 v216, v84
	s_waitcnt lgkmcnt(5)
	v_mfma_f32_32x32x16_bf16 v[66:81], v[234:237], v[146:149], v[66:81]
	ds_read2_b64 v[234:237], v3 offset0:132 offset1:134
	v_exp_f32_e32 v217, v85
	v_exp_f32_e32 v218, v86
	v_exp_f32_e32 v219, v87
	s_waitcnt lgkmcnt(5)
	v_mfma_f32_32x32x16_bf16 v[66:81], v[238:241], v[126:129], v[66:81]
	ds_read2_b64 v[238:241], v0 offset0:164 offset1:166
	v_exp_f32_e32 v220, v88
	v_exp_f32_e32 v221, v89
	v_max3_f32 v159, v82, v83, v84
	v_max3_f32 v250, v85, v86, v87
	s_waitcnt lgkmcnt(5)
	v_mfma_f32_32x32x16_bf16 v[66:81], v[242:245], v[122:125], v[66:81]
	ds_read2_b64 v[242:245], v3 offset0:136 offset1:138
	v_exp_f32_e32 v222, v90
	v_exp_f32_e32 v223, v91
	v_exp_f32_e32 v224, v92
	s_waitcnt lgkmcnt(5)
	v_mfma_f32_32x32x16_bf16 v[66:81], v[246:249], v[118:121], v[66:81]
	ds_read2_b64 v[246:249], v0 offset0:168 offset1:170
	s_setprio 0
	v_exp_f32_e32 v225, v93
	v_exp_f32_e32 v12, v94
	v_exp_f32_e32 v13, v95
	v_exp_f32_e32 v14, v96
	v_exp_f32_e32 v15, v97
	v_max3_f32 v159, v159, v88, v89
	v_max3_f32 v250, v250, v90, v91
	v_max3_f32 v159, v159, v92, v93
	v_max3_f32 v250, v250, v94, v95
	v_max3_f32 v159, v159, v96, v97
	s_nop 1
	v_max3_f32 v159, v159, v66, v67
	v_max3_f32 v250, v250, v68, v69
	v_max3_f32 v159, v159, v70, v71
	v_max3_f32 v250, v250, v72, v73
	v_max3_f32 v159, v159, v74, v75
	v_max3_f32 v250, v250, v76, v77
	v_max3_f32 v159, v159, v78, v79
	v_max3_f32 v250, v250, v80, v81
	v_max_f32_e32 v0, v159, v250
	v_mov_b32_e32 v3, v0
	s_nop 1
	v_permlane32_swap_b32_e32 v0, v3
	v_max_f32_e32 v0, v0, v3
	s_nop 0
	v_cmp_lt_f32_e32 vcc, s30, v0
	s_cbranch_vccnz .Lat_r0

; DI int crow(int r, int hi) { return (r & 3) + 8 * (r >> 2) + 4 * hi; }
; DI void attn_tile(bool MASK, const LAS unsigned char* Ks, const LAS unsigned char* Vs, const bf16x8 (&qr)[6], f32x16& negm, float& mrun, float& lrun, f32x16& o0, f32x16& o1,
;                                        int kv0, int qrow, int r32, int hi) {
;     ...
;     if (MASK) {
;         asm volatile("" ::: "memory");
; #pragma unroll
;         for (int r = 0; r < 16; ++r) { const int kv = kv0 + crow(r, hi); if (kv > qrow) p0[r] = -INFINITY; if (kv + 32 > qrow) p1[r] = -INFINITY; }
;     }
.Lkf_skip0:
	s_waitcnt vmcnt(3)
	ds_write_b128 v209, v[130:133] offset:22016
	ds_write_b128 v210, v[106:109] offset:22016
	ds_write2_b64 v0, v[110:111], v[112:113] offset1:1
	s_ashr_i32 s35, s34, 31
	global_load_dwordx4 v[130:133], v[246:247], off
	global_load_dwordx4 v[106:109], v[248:249], off
	v_lshl_add_u64 v[246:247], s[34:35], 1, v[192:193]
	global_load_dwordx4 v[110:113], v[246:247], off
	s_branch .LBB0_855
.Lat_m0:
	s_waitcnt lgkmcnt(8)
	v_mfma_f32_32x32x16_bf16 v[66:81], v[226:229], v[154:157], v[50:65]
	s_waitcnt lgkmcnt(7)
	v_mfma_f32_32x32x16_bf16 v[66:81], v[230:233], v[150:153], v[66:81]
	s_waitcnt lgkmcnt(3)
	v_mfma_f32_32x32x16_bf16 v[66:81], v[234:237], v[146:149], v[66:81]
	s_waitcnt lgkmcnt(2)
	v_mfma_f32_32x32x16_bf16 v[66:81], v[238:241], v[126:129], v[66:81]
	s_waitcnt lgkmcnt(1)
	v_mfma_f32_32x32x16_bf16 v[66:81], v[242:245], v[122:125], v[66:81]
	s_waitcnt lgkmcnt(0)
	v_mfma_f32_32x32x16_bf16 v[66:81], v[246:249], v[118:121], v[66:81]
	s_setprio 0
	v_add_u32_e32 v3, v205, v208
	v_add_u32_e32 v0, 0x4000, v3
	v_add_u32_e32 v3, 0x3000, v3
	ds_read2_b64 v[214:217], v3 offset0:128 offset1:130
	ds_read2_b64 v[218:221], v0 offset0:160 offset1:162
	ds_read2_b64 v[222:225], v3 offset0:132 offset1:134
	ds_read2_b64 v[226:229], v0 offset0:164 offset1:166
	ds_read2_b64 v[230:233], v3 offset0:136 offset1:138
	ds_read2_b64 v[234:237], v0 offset0:168 offset1:170
	ds_read2_b64 v[238:241], v3 offset0:140 offset1:142
	ds_read2_b64 v[242:245], v0 offset0:172 offset1:174
	v_add_u32_e32 v0, s21, v207
	v_add_u32_e32 v3, 32, v0
	v_cmp_le_i32_e32 vcc, v3, v49
	v_add_u32_e32 v3, 33, v0
	s_nop 5
	v_cndmask_b32_e32 v66, v212, v66, vcc
	v_cmp_lt_i32_e32 vcc, v0, v49
	s_nop 1
	v_cndmask_b32_e32 v83, v212, v83, vcc
	v_cmp_le_i32_e32 vcc, v0, v49
	s_nop 1
	v_cndmask_b32_e32 v82, v212, v82, vcc
	v_cmp_le_i32_e32 vcc, v3, v49
	v_add_u32_e32 v3, 2, v0
	s_nop 0
	v_cndmask_b32_e32 v67, v212, v67, vcc
	v_cmp_le_i32_e32 vcc, v3, v49
	v_add_u32_e32 v3, 34, v0
	s_nop 0
	v_cndmask_b32_e32 v84, v212, v84, vcc
	v_cmp_le_i32_e32 vcc, v3, v49
	v_add_u32_e32 v3, 3, v0
	s_nop 0
	v_cndmask_b32_e32 v68, v212, v68, vcc
	v_cmp_le_i32_e32 vcc, v3, v49
	v_add_u32_e32 v3, 35, v0
	s_nop 0
	v_cndmask_b32_e32 v85, v212, v85, vcc
	v_cmp_le_i32_e32 vcc, v3, v49
	v_add_u32_e32 v3, 8, v0
	s_nop 0
	v_cndmask_b32_e32 v69, v212, v69, vcc
	v_cmp_le_i32_e32 vcc, v3, v49
	v_add_u32_e32 v3, 40, v0
	s_nop 0
	v_cndmask_b32_e32 v86, v212, v86, vcc
	v_cmp_le_i32_e32 vcc, v3, v49
	v_add_u32_e32 v3, 9, v0
	s_nop 0
	v_cndmask_b32_e32 v70, v212, v70, vcc
	v_cmp_le_i32_e32 vcc, v3, v49
	v_add_u32_e32 v3, 41, v0
	s_nop 0
	v_cndmask_b32_e32 v87, v212, v87, vcc
	v_cmp_le_i32_e32 vcc, v3, v49
	v_add_u32_e32 v3, 10, v0
	s_nop 0
	v_cndmask_b32_e32 v71, v212, v71, vcc
	v_cmp_le_i32_e32 vcc, v3, v49
	v_add_u32_e32 v3, 42, v0
	s_nop 0
	v_cndmask_b32_e32 v88, v212, v88, vcc
	v_cmp_le_i32_e32 vcc, v3, v49
	v_add_u32_e32 v3, 11, v0
	s_nop 0
	v_cndmask_b32_e32 v72, v212, v72, vcc
	v_cmp_le_i32_e32 vcc, v3, v49
	v_add_u32_e32 v3, 43, v0
	s_nop 0
	v_cndmask_b32_e32 v89, v212, v89, vcc
	v_cmp_le_i32_e32 vcc, v3, v49
	v_add_u32_e32 v3, 16, v0
	s_nop 0
	v_cndmask_b32_e32 v73, v212, v73, vcc
	v_cmp_le_i32_e32 vcc, v3, v49
	v_add_u32_e32 v3, 48, v0
	s_nop 0
	v_cndmask_b32_e32 v90, v212, v90, vcc
	v_cmp_le_i32_e32 vcc, v3, v49
	v_add_u32_e32 v3, 17, v0
	s_nop 0
	v_cndmask_b32_e32 v74, v212, v74, vcc
	v_cmp_le_i32_e32 vcc, v3, v49
	v_add_u32_e32 v3, 49, v0
	s_nop 0
	v_cndmask_b32_e32 v91, v212, v91, vcc
	v_cmp_le_i32_e32 vcc, v3, v49
	v_add_u32_e32 v3, 18, v0
	s_nop 0
	v_cndmask_b32_e32 v75, v212, v75, vcc
	v_cmp_le_i32_e32 vcc, v3, v49
	v_add_u32_e32 v3, 50, v0
	s_nop 0
	v_cndmask_b32_e32 v92, v212, v92, vcc
	v_cmp_le_i32_e32 vcc, v3, v49
	v_add_u32_e32 v3, 19, v0
	s_nop 0
	v_cndmask_b32_e32 v76, v212, v76, vcc
	v_cmp_le_i32_e32 vcc, v3, v49
	v_add_u32_e32 v3, 51, v0
	s_nop 0
	v_cndmask_b32_e32 v93, v212, v93, vcc
	v_cmp_le_i32_e32 vcc, v3, v49
	v_add_u32_e32 v3, 24, v0
	s_nop 0
	v_cndmask_b32_e32 v77, v212, v77, vcc
	v_cmp_le_i32_e32 vcc, v3, v49
	v_add_u32_e32 v3, 56, v0
	s_nop 0
	v_cndmask_b32_e32 v94, v212, v94, vcc
	v_cmp_le_i32_e32 vcc, v3, v49
	v_add_u32_e32 v3, 25, v0
	s_nop 0
	v_cndmask_b32_e32 v78, v212, v78, vcc
	v_cmp_le_i32_e32 vcc, v3, v49
	v_add_u32_e32 v3, 57, v0
	s_nop 0
	v_cndmask_b32_e32 v95, v212, v95, vcc
	v_cmp_le_i32_e32 vcc, v3, v49
	v_add_u32_e32 v3, 26, v0
	s_nop 0
	v_cndmask_b32_e32 v79, v212, v79, vcc
	v_cmp_le_i32_e32 vcc, v3, v49
	v_add_u32_e32 v3, 58, v0
	s_nop 0
	v_cndmask_b32_e32 v96, v212, v96, vcc
	v_cmp_le_i32_e32 vcc, v3, v49
	v_add_u32_e32 v3, 27, v0
	v_add_u32_e32 v0, 59, v0
	v_cndmask_b32_e32 v80, v212, v80, vcc
	v_cmp_le_i32_e32 vcc, v3, v49
	s_nop 1
	v_cndmask_b32_e32 v97, v212, v97, vcc
	v_cmp_le_i32_e32 vcc, v0, v49
	s_nop 1
	v_cndmask_b32_e32 v81, v212, v81, vcc

; #define LAS __attribute__((address_space(3)))
; DI void attn_tile(bool MASK, const LAS unsigned char* Ks, const LAS unsigned char* Vs, const bf16x8 (&qr)[6], f32x16& negm, float& mrun, float& lrun, f32x16& o0, f32x16& o1,
;                                        int kv0, int qrow, int r32, int hi) {
;     f32x16 p0, p1;
;     __builtin_amdgcn_s_setprio(1);
;     {
;         const bf16x8 a0 = *(const LAS bf16x8*)(Ks + r32 * 208 + hi * 16);
;         const bf16x8 a1 = *(const LAS bf16x8*)(Ks + (32 + r32) * 208 + hi * 16);
;         p0 = MFMA32(a0, qr[0], negm); p1 = MFMA32(a1, qr[0], negm);
;     }
; #pragma unroll
;     for (int d0 = 1; d0 < 6; ++d0) {
;         const bf16x8 a0 = *(const LAS bf16x8*)(Ks + r32 * 208 + (2 * d0 + hi) * 16);
;         const bf16x8 a1 = *(const LAS bf16x8*)(Ks + (32 + r32) * 208 + (2 * d0 + hi) * 16);
;         p0 = MFMA32(a0, qr[d0], p0); p1 = MFMA32(a1, qr[d0], p1);
;     }
;     __builtin_amdgcn_s_setprio(0);
;     if (MASK) {
;         asm volatile("" ::: "memory");
; #pragma unroll
;         for (int r = 0; r < 16; ++r) { const int kv = kv0 + crow(r, hi); if (kv > qrow) p0[r] = -INFINITY; if (kv + 32 > qrow) p1[r] = -INFINITY; }
;     }
;     float mxa = max3f(p0[0], p0[1], p1[0]), mxb = max3f(p0[2], p0[3], p1[1]); mxa = max3f(mxa, p1[2], p1[3]);
; #pragma unroll
;     for (int r = 4; r < 16; r += 4) { mxa = max3f(mxa, p0[r], p0[r + 1]); mxb = max3f(mxb, p0[r + 2], p0[r + 3]); mxa = max3f(mxa, p1[r], p1[r + 1]); mxb = max3f(mxb, p1[r + 2], p1[r + 3]); }
;     float mx = max2f(mxa, mxb);
;     mx = max2f(mx, __shfl_xor(mx, 32));
;     if (__any(mx > AT_THR)) {
;         const float dm = max2f(mx, 0.f);
;         const float alpha = __builtin_amdgcn_exp2f(-dm);
;         mrun += dm; lrun *= alpha;
; #pragma unroll
;         for (int r = 0; r < 16; ++r) { o0[r] *= alpha; o1[r] *= alpha; p0[r] -= dm; p1[r] -= dm; negm[r] = -mrun; }
;     }
;     float ls = 0.f;
; #pragma unroll
;     for (int r = 0; r < 16; ++r) { p0[r] = __builtin_amdgcn_exp2f(p0[r]); p1[r] = __builtin_amdgcn_exp2f(p1[r]); ls += p0[r] + p1[r]; }
;     lrun += ls;
; DI void attn_unit(int b, int h, int qb, const bf16* Qb, const bf16* Kb, const bf16* Vt, const int* positions, bf16* O, LAS unsigned char* lds, int tid) {
;     ...
;         __syncthreads();
;         AT_COMMIT(C, 2); AT_ISSUE(C, t + 5);
;         AT_TILE(t + 1, 1);
.LBB0_855:
	s_add_i32 s33, s23, 5
	s_min_i32 s33, s33, s20
	v_mad_i64_i32 v[246:247], s[34:35], s33, v161, v[190:191]
	v_mad_i64_i32 v[248:249], s[34:35], s33, v161, v[194:195]
	v_add3_u32 v0, v204, v199, s31
	s_lshl_b32 s34, s33, 6
	s_waitcnt lgkmcnt(0)
	s_barrier
	s_add_i32 s98, s23, 1
	s_cmp_ge_i32 s98, s19
	s_cbranch_scc1 .Lkf_skip1
	s_add_i32 s98, s21, 64
	s_cmp_gt_i32 s98, s22
	s_cbranch_scc1 .Lkf_skip1
	v_add_u32_e32 v3, v206, v160
	ds_read_b128 v[4:7], v3 offset:22016
	ds_read_b128 v[8:11], v3 offset:22048
	ds_read_b128 v[12:15], v3 offset:22080
	ds_read_b128 v[214:217], v3 offset:22112
	ds_read_b128 v[218:221], v3 offset:22144
	ds_read_b128 v[222:225], v3 offset:22176
	ds_read_b128 v[226:229], v3 offset:28672
	ds_read_b128 v[230:233], v3 offset:28704
	ds_write_b128 v209, v[98:101] offset:44032
	ds_write_b128 v210, v[102:105] offset:44032
	ds_write2_b64 v0, v[114:115], v[116:117] offset1:1
	s_ashr_i32 s35, s34, 31
	global_load_dwordx4 v[98:101], v[246:247], off
	global_load_dwordx4 v[102:105], v[248:249], off
	v_lshl_add_u64 v[246:247], s[34:35], 1, v[192:193]
	global_load_dwordx4 v[114:117], v[246:247], off
	s_add_i32 s33, s23, 1
	s_cmp_lt_i32 s33, s12
	s_setprio 1
	s_waitcnt lgkmcnt(10)
	v_mfma_f32_32x32x16_bf16 v[82:97], v[4:7], v[154:157], v[50:65]
	ds_read_b128 v[234:237], v3 offset:28736
	s_waitcnt lgkmcnt(10)
	v_mfma_f32_32x32x16_bf16 v[82:97], v[8:11], v[150:153], v[82:97]
	ds_read_b128 v[238:241], v3 offset:28768
	s_waitcnt lgkmcnt(10)
	v_mfma_f32_32x32x16_bf16 v[82:97], v[12:15], v[146:149], v[82:97]
	ds_read_b128 v[242:245], v3 offset:28800
	s_waitcnt lgkmcnt(10)
	v_mfma_f32_32x32x16_bf16 v[82:97], v[214:217], v[126:129], v[82:97]
	ds_read_b128 v[246:249], v3 offset:28832
	s_waitcnt lgkmcnt(10)
	v_mfma_f32_32x32x16_bf16 v[82:97], v[218:221], v[122:125], v[82:97]
	s_waitcnt lgkmcnt(9)
	v_mfma_f32_32x32x16_bf16 v[82:97], v[222:225], v[118:121], v[82:97]
	s_cbranch_scc0 .Lat_m1
	s_setprio 0
	v_add_u32_e32 v3, v205, v208
	v_add_u32_e32 v0, 0x9800, v3
	v_add_u32_e32 v3, 0x8800, v3
	s_waitcnt lgkmcnt(8)
	v_mfma_f32_32x32x16_bf16 v[66:81], v[226:229], v[154:157], v[50:65]
	ds_read2_b64 v[226:229], v3 offset0:64 offset1:66
	s_waitcnt lgkmcnt(8)
	v_mfma_f32_32x32x16_bf16 v[66:81], v[230:233], v[150:153], v[66:81]
	ds_read2_b64 v[230:233], v0 offset0:96 offset1:98
	s_nop 3
	v_exp_f32_e32 v214, v82
	v_exp_f32_e32 v215, v83
	v_exp_f32_e32 v216, v84
	s_waitcnt lgkmcnt(5)
	v_mfma_f32_32x32x16_bf16 v[66:81], v[234:237], v[146:149], v[66:81]
	ds_read2_b64 v[234:237], v3 offset0:68 offset1:70
	v_exp_f32_e32 v217, v85
	v_exp_f32_e32 v218, v86
	v_exp_f32_e32 v219, v87
	s_waitcnt lgkmcnt(5)
	v_mfma_f32_32x32x16_bf16 v[66:81], v[238:241], v[126:129], v[66:81]
	ds_read2_b64 v[238:241], v0 offset0:100 offset1:102
	v_exp_f32_e32 v220, v88
	v_exp_f32_e32 v221, v89
	v_max3_f32 v159, v82, v83, v84
	v_max3_f32 v250, v85, v86, v87
	s_waitcnt lgkmcnt(5)
	v_mfma_f32_32x32x16_bf16 v[66:81], v[242:245], v[122:125], v[66:81]
	ds_read2_b64 v[242:245], v3 offset0:72 offset1:74
	v_exp_f32_e32 v222, v90
	v_exp_f32_e32 v223, v91
	v_exp_f32_e32 v224, v92
	s_waitcnt lgkmcnt(5)
	v_mfma_f32_32x32x16_bf16 v[66:81], v[246:249], v[118:121], v[66:81]
	ds_read2_b64 v[246:249], v0 offset0:104 offset1:106
	s_setprio 0
	v_exp_f32_e32 v225, v93
	v_exp_f32_e32 v12, v94
	v_exp_f32_e32 v13, v95
	v_exp_f32_e32 v14, v96
	v_exp_f32_e32 v15, v97
	v_max3_f32 v159, v159, v88, v89
	v_max3_f32 v250, v250, v90, v91
	v_max3_f32 v159, v159, v92, v93
	v_max3_f32 v250, v250, v94, v95
	v_max3_f32 v159, v159, v96, v97
	s_nop 1
	v_max3_f32 v159, v159, v66, v67
	v_max3_f32 v250, v250, v68, v69
	v_max3_f32 v159, v159, v70, v71
	v_max3_f32 v250, v250, v72, v73
	v_max3_f32 v159, v159, v74, v75
	v_max3_f32 v250, v250, v76, v77
	v_max3_f32 v159, v159, v78, v79
	v_max3_f32 v250, v250, v80, v81
	v_max_f32_e32 v0, v159, v250
	v_mov_b32_e32 v3, v0
	s_nop 1
	v_permlane32_swap_b32_e32 v0, v3
	v_max_f32_e32 v0, v0, v3
	s_nop 0
	v_cmp_lt_f32_e32 vcc, s30, v0
	s_cbranch_vccnz .Lat_r1

; DI int crow(int r, int hi) { return (r & 3) + 8 * (r >> 2) + 4 * hi; }
; DI void attn_tile(bool MASK, const LAS unsigned char* Ks, const LAS unsigned char* Vs, const bf16x8 (&qr)[6], f32x16& negm, float& mrun, float& lrun, f32x16& o0, f32x16& o1,
;                                        int kv0, int qrow, int r32, int hi) {
;     ...
;     if (MASK) {
;         asm volatile("" ::: "memory");
; #pragma unroll
;         for (int r = 0; r < 16; ++r) { const int kv = kv0 + crow(r, hi); if (kv > qrow) p0[r] = -INFINITY; if (kv + 32 > qrow) p1[r] = -INFINITY; }
;     }
.Lkf_skip1:
	ds_write_b128 v209, v[98:101] offset:44032
	ds_write_b128 v210, v[102:105] offset:44032
	ds_write2_b64 v0, v[114:115], v[116:117] offset1:1
	s_ashr_i32 s35, s34, 31
	global_load_dwordx4 v[98:101], v[246:247], off
	global_load_dwordx4 v[102:105], v[248:249], off
	v_lshl_add_u64 v[246:247], s[34:35], 1, v[192:193]
	global_load_dwordx4 v[114:117], v[246:247], off
	s_branch .LBB0_862
.Lat_m1:
	s_waitcnt lgkmcnt(8)
	v_mfma_f32_32x32x16_bf16 v[66:81], v[226:229], v[154:157], v[50:65]
	s_waitcnt lgkmcnt(7)
	v_mfma_f32_32x32x16_bf16 v[66:81], v[230:233], v[150:153], v[66:81]
	s_waitcnt lgkmcnt(3)
	v_mfma_f32_32x32x16_bf16 v[66:81], v[234:237], v[146:149], v[66:81]
	s_waitcnt lgkmcnt(2)
	v_mfma_f32_32x32x16_bf16 v[66:81], v[238:241], v[126:129], v[66:81]
	s_waitcnt lgkmcnt(1)
	v_mfma_f32_32x32x16_bf16 v[66:81], v[242:245], v[122:125], v[66:81]
	s_waitcnt lgkmcnt(0)
	v_mfma_f32_32x32x16_bf16 v[66:81], v[246:249], v[118:121], v[66:81]
	s_setprio 0
	v_add_u32_e32 v3, v205, v208
	v_add_u32_e32 v0, 0x9800, v3
	v_add_u32_e32 v3, 0x8800, v3
	ds_read2_b64 v[214:217], v3 offset0:64 offset1:66
	ds_read2_b64 v[218:221], v0 offset0:96 offset1:98
	ds_read2_b64 v[222:225], v3 offset0:68 offset1:70
	ds_read2_b64 v[226:229], v0 offset0:100 offset1:102
	ds_read2_b64 v[230:233], v3 offset0:72 offset1:74
	ds_read2_b64 v[234:237], v0 offset0:104 offset1:106
	ds_read2_b64 v[238:241], v3 offset0:76 offset1:78
	ds_read2_b64 v[242:245], v0 offset0:108 offset1:110
	v_add_u32_e32 v0, s21, v207
	v_add_u32_e32 v4, 0x60, v0
	v_add_u32_e32 v3, 64, v0
	v_cmp_le_i32_e32 vcc, v4, v49
	s_nop 5
	v_cndmask_b32_e32 v66, v212, v66, vcc
	v_cmp_lt_i32_e32 vcc, v3, v49
	s_nop 1
	v_cndmask_b32_e32 v83, v212, v83, vcc
	v_cmp_le_i32_e32 vcc, v3, v49
	v_add_u32_e32 v3, 0x61, v0
	s_nop 0
	v_cndmask_b32_e32 v82, v212, v82, vcc
	v_cmp_le_i32_e32 vcc, v3, v49
	v_add_u32_e32 v3, 0x42, v0
	s_nop 0
	v_cndmask_b32_e32 v67, v212, v67, vcc
	v_cmp_le_i32_e32 vcc, v3, v49
	v_add_u32_e32 v3, 0x62, v0
	s_nop 0
	v_cndmask_b32_e32 v84, v212, v84, vcc
	v_cmp_le_i32_e32 vcc, v3, v49
	v_add_u32_e32 v3, 0x43, v0
	s_nop 0
	v_cndmask_b32_e32 v68, v212, v68, vcc
	v_cmp_le_i32_e32 vcc, v3, v49
	v_add_u32_e32 v3, 0x63, v0
	s_nop 0
	v_cndmask_b32_e32 v85, v212, v85, vcc
	v_cmp_le_i32_e32 vcc, v3, v49
	v_add_u32_e32 v3, 0x48, v0
	s_nop 0
	v_cndmask_b32_e32 v69, v212, v69, vcc
	v_cmp_le_i32_e32 vcc, v3, v49
	v_add_u32_e32 v3, 0x68, v0
	s_nop 0
	v_cndmask_b32_e32 v86, v212, v86, vcc
	v_cmp_le_i32_e32 vcc, v3, v49
	v_add_u32_e32 v3, 0x49, v0
	s_nop 0
	v_cndmask_b32_e32 v70, v212, v70, vcc
	v_cmp_le_i32_e32 vcc, v3, v49
	v_add_u32_e32 v3, 0x69, v0
	s_nop 0
	v_cndmask_b32_e32 v87, v212, v87, vcc
	v_cmp_le_i32_e32 vcc, v3, v49
	v_add_u32_e32 v3, 0x4a, v0
	s_nop 0
	v_cndmask_b32_e32 v71, v212, v71, vcc
	v_cmp_le_i32_e32 vcc, v3, v49
	v_add_u32_e32 v3, 0x6a, v0
	s_nop 0
	v_cndmask_b32_e32 v88, v212, v88, vcc
	v_cmp_le_i32_e32 vcc, v3, v49
	v_add_u32_e32 v3, 0x4b, v0
	s_nop 0
	v_cndmask_b32_e32 v72, v212, v72, vcc
	v_cmp_le_i32_e32 vcc, v3, v49
	v_add_u32_e32 v3, 0x6b, v0
	s_nop 0
	v_cndmask_b32_e32 v89, v212, v89, vcc
	v_cmp_le_i32_e32 vcc, v3, v49
	v_add_u32_e32 v3, 0x50, v0
	s_nop 0
	v_cndmask_b32_e32 v73, v212, v73, vcc
	v_cmp_le_i32_e32 vcc, v3, v49
	v_add_u32_e32 v3, 0x70, v0
	s_nop 0
	v_cndmask_b32_e32 v90, v212, v90, vcc
	v_cmp_le_i32_e32 vcc, v3, v49
	v_add_u32_e32 v3, 0x51, v0
	s_nop 0
	v_cndmask_b32_e32 v74, v212, v74, vcc
	v_cmp_le_i32_e32 vcc, v3, v49
	v_add_u32_e32 v3, 0x71, v0
	s_nop 0
	v_cndmask_b32_e32 v91, v212, v91, vcc
	v_cmp_le_i32_e32 vcc, v3, v49
	v_add_u32_e32 v3, 0x52, v0
	s_nop 0
	v_cndmask_b32_e32 v75, v212, v75, vcc
	v_cmp_le_i32_e32 vcc, v3, v49
	v_add_u32_e32 v3, 0x72, v0
	s_nop 0
	v_cndmask_b32_e32 v92, v212, v92, vcc
	v_cmp_le_i32_e32 vcc, v3, v49
	v_add_u32_e32 v3, 0x53, v0
	s_nop 0
	v_cndmask_b32_e32 v76, v212, v76, vcc
	v_cmp_le_i32_e32 vcc, v3, v49
	v_add_u32_e32 v3, 0x73, v0
	s_nop 0
	v_cndmask_b32_e32 v93, v212, v93, vcc
	v_cmp_le_i32_e32 vcc, v3, v49
	v_add_u32_e32 v3, 0x58, v0
	s_nop 0
	v_cndmask_b32_e32 v77, v212, v77, vcc
	v_cmp_le_i32_e32 vcc, v3, v49
	v_add_u32_e32 v3, 0x78, v0
	s_nop 0
	v_cndmask_b32_e32 v94, v212, v94, vcc
	v_cmp_le_i32_e32 vcc, v3, v49
	v_add_u32_e32 v3, 0x59, v0
	s_nop 0
	v_cndmask_b32_e32 v78, v212, v78, vcc
	v_cmp_le_i32_e32 vcc, v3, v49
	v_add_u32_e32 v3, 0x79, v0
	s_nop 0
	v_cndmask_b32_e32 v95, v212, v95, vcc
	v_cmp_le_i32_e32 vcc, v3, v49
	v_add_u32_e32 v3, 0x5a, v0
	s_nop 0
	v_cndmask_b32_e32 v79, v212, v79, vcc
	v_cmp_le_i32_e32 vcc, v3, v49
	v_add_u32_e32 v3, 0x7a, v0
	s_nop 0
	v_cndmask_b32_e32 v96, v212, v96, vcc
	v_cmp_le_i32_e32 vcc, v3, v49
	v_add_u32_e32 v3, 0x5b, v0
	v_add_u32_e32 v0, 0x7b, v0
	v_cndmask_b32_e32 v80, v212, v80, vcc
	v_cmp_le_i32_e32 vcc, v3, v49
	s_nop 1
	v_cndmask_b32_e32 v97, v212, v97, vcc
	v_cmp_le_i32_e32 vcc, v0, v49
	s_nop 1
	v_cndmask_b32_e32 v81, v212, v81, vcc

; #define LAS __attribute__((address_space(3)))
; DI void attn_tile(bool MASK, const LAS unsigned char* Ks, const LAS unsigned char* Vs, const bf16x8 (&qr)[6], f32x16& negm, float& mrun, float& lrun, f32x16& o0, f32x16& o1,
;                                        int kv0, int qrow, int r32, int hi) {
;     f32x16 p0, p1;
;     __builtin_amdgcn_s_setprio(1);
;     {
;         const bf16x8 a0 = *(const LAS bf16x8*)(Ks + r32 * 208 + hi * 16);
;         const bf16x8 a1 = *(const LAS bf16x8*)(Ks + (32 + r32) * 208 + hi * 16);
;         p0 = MFMA32(a0, qr[0], negm); p1 = MFMA32(a1, qr[0], negm);
;     }
; #pragma unroll
;     for (int d0 = 1; d0 < 6; ++d0) {
;         const bf16x8 a0 = *(const LAS bf16x8*)(Ks + r32 * 208 + (2 * d0 + hi) * 16);
;         const bf16x8 a1 = *(const LAS bf16x8*)(Ks + (32 + r32) * 208 + (2 * d0 + hi) * 16);
;         p0 = MFMA32(a0, qr[d0], p0); p1 = MFMA32(a1, qr[d0], p1);
;     }
;     __builtin_amdgcn_s_setprio(0);
;     if (MASK) {
;         asm volatile("" ::: "memory");
; #pragma unroll
;         for (int r = 0; r < 16; ++r) { const int kv = kv0 + crow(r, hi); if (kv > qrow) p0[r] = -INFINITY; if (kv + 32 > qrow) p1[r] = -INFINITY; }
;     }
;     float mxa = max3f(p0[0], p0[1], p1[0]), mxb = max3f(p0[2], p0[3], p1[1]); mxa = max3f(mxa, p1[2], p1[3]);
; #pragma unroll
;     for (int r = 4; r < 16; r += 4) { mxa = max3f(mxa, p0[r], p0[r + 1]); mxb = max3f(mxb, p0[r + 2], p0[r + 3]); mxa = max3f(mxa, p1[r], p1[r + 1]); mxb = max3f(mxb, p1[r + 2], p1[r + 3]); }
;     float mx = max2f(mxa, mxb);
;     mx = max2f(mx, __shfl_xor(mx, 32));
;     if (__any(mx > AT_THR)) {
;         const float dm = max2f(mx, 0.f);
;         const float alpha = __builtin_amdgcn_exp2f(-dm);
;         mrun += dm; lrun *= alpha;
; #pragma unroll
;         for (int r = 0; r < 16; ++r) { o0[r] *= alpha; o1[r] *= alpha; p0[r] -= dm; p1[r] -= dm; negm[r] = -mrun; }
;     }
;     float ls = 0.f;
; #pragma unroll
;     for (int r = 0; r < 16; ++r) { p0[r] = __builtin_amdgcn_exp2f(p0[r]); p1[r] = __builtin_amdgcn_exp2f(p1[r]); ls += p0[r] + p1[r]; }
;     lrun += ls;
; DI void attn_unit(int b, int h, int qb, const bf16* Qb, const bf16* Kb, const bf16* Vt, const int* positions, bf16* O, LAS unsigned char* lds, int tid) {
;     ...
;         __syncthreads();
;         AT_COMMIT(A, 0); AT_ISSUE(A, t + 6);
;         AT_TILE(t + 2, 2);
.LBB0_862:
	s_add_i32 s33, s23, 6
	s_min_i32 s33, s33, s20
	v_mad_i64_i32 v[246:247], s[34:35], s33, v161, v[190:191]
	v_mad_i64_i32 v[248:249], s[34:35], s33, v161, v[194:195]
	s_lshl_b32 s34, s33, 6
	s_waitcnt lgkmcnt(0)
	s_barrier
	s_add_i32 s98, s23, 2
	s_cmp_ge_i32 s98, s19
	s_cbranch_scc1 .Lkf_skip2
	s_add_i32 s98, s21, 0x80
	s_cmp_gt_i32 s98, s22
	s_cbranch_scc1 .Lkf_skip2
	v_add_u32_e32 v3, v206, v160
	ds_read_b128 v[4:7], v3 offset:44032
	ds_read_b128 v[8:11], v3 offset:44064
	ds_read_b128 v[12:15], v3 offset:44096
	ds_read_b128 v[214:217], v3 offset:44128
	ds_read_b128 v[218:221], v3 offset:44160
	ds_read_b128 v[222:225], v3 offset:44192
	ds_read_b128 v[226:229], v3 offset:50688
	ds_read_b128 v[230:233], v3 offset:50720
	s_waitcnt vmcnt(6)
	ds_write_b128 v209, v[142:145]
	ds_write_b128 v210, v[138:141]
	ds_write2_b64 v211, v[134:135], v[136:137] offset1:1
	s_ashr_i32 s35, s34, 31
	global_load_dwordx4 v[142:145], v[246:247], off
	global_load_dwordx4 v[138:141], v[248:249], off
	v_lshl_add_u64 v[246:247], s[34:35], 1, v[192:193]
	global_load_dwordx4 v[134:137], v[246:247], off
	s_add_i32 s33, s23, 2
	s_cmp_lt_i32 s33, s12
	s_setprio 1
	s_waitcnt lgkmcnt(10)
	v_mfma_f32_32x32x16_bf16 v[82:97], v[4:7], v[154:157], v[50:65]
	ds_read_b128 v[234:237], v3 offset:50752
	s_waitcnt lgkmcnt(10)
	v_mfma_f32_32x32x16_bf16 v[82:97], v[8:11], v[150:153], v[82:97]
	ds_read_b128 v[238:241], v3 offset:50784
	s_waitcnt lgkmcnt(10)
	v_mfma_f32_32x32x16_bf16 v[82:97], v[12:15], v[146:149], v[82:97]
	ds_read_b128 v[242:245], v3 offset:50816
	s_waitcnt lgkmcnt(10)
	v_mfma_f32_32x32x16_bf16 v[82:97], v[214:217], v[126:129], v[82:97]
	ds_read_b128 v[246:249], v3 offset:50848
	s_waitcnt lgkmcnt(10)
	v_mfma_f32_32x32x16_bf16 v[82:97], v[218:221], v[122:125], v[82:97]
	s_waitcnt lgkmcnt(9)
	v_mfma_f32_32x32x16_bf16 v[82:97], v[222:225], v[118:121], v[82:97]
	s_cbranch_scc0 .Lat_m2
	s_setprio 0
	v_add_u32_e32 v3, v205, v208
	v_add_u32_e32 v0, 0xf000, v3
	v_add_u32_e32 v3, 0xe000, v3
	s_waitcnt lgkmcnt(8)
	v_mfma_f32_32x32x16_bf16 v[66:81], v[226:229], v[154:157], v[50:65]
	ds_read2_b64 v[226:229], v3 offset1:2
	s_waitcnt lgkmcnt(8)
	v_mfma_f32_32x32x16_bf16 v[66:81], v[230:233], v[150:153], v[66:81]
	ds_read2_b64 v[230:233], v0 offset0:32 offset1:34
	s_nop 3
	v_exp_f32_e32 v214, v82
	v_exp_f32_e32 v215, v83
	v_exp_f32_e32 v216, v84
	s_waitcnt lgkmcnt(5)
	v_mfma_f32_32x32x16_bf16 v[66:81], v[234:237], v[146:149], v[66:81]
	ds_read2_b64 v[234:237], v3 offset0:4 offset1:6
	v_exp_f32_e32 v217, v85
	v_exp_f32_e32 v218, v86
	v_exp_f32_e32 v219, v87
	s_waitcnt lgkmcnt(5)
	v_mfma_f32_32x32x16_bf16 v[66:81], v[238:241], v[126:129], v[66:81]
	ds_read2_b64 v[238:241], v0 offset0:36 offset1:38
	v_exp_f32_e32 v220, v88
	v_exp_f32_e32 v221, v89
	v_max3_f32 v159, v82, v83, v84
	v_max3_f32 v250, v85, v86, v87
	s_waitcnt lgkmcnt(5)
	v_mfma_f32_32x32x16_bf16 v[66:81], v[242:245], v[122:125], v[66:81]
	ds_read2_b64 v[242:245], v3 offset0:8 offset1:10
	v_exp_f32_e32 v222, v90
	v_exp_f32_e32 v223, v91
	v_exp_f32_e32 v224, v92
	s_waitcnt lgkmcnt(5)
	v_mfma_f32_32x32x16_bf16 v[66:81], v[246:249], v[118:121], v[66:81]
	ds_read2_b64 v[246:249], v0 offset0:40 offset1:42
	s_setprio 0
	v_exp_f32_e32 v225, v93
	v_exp_f32_e32 v12, v94
	v_exp_f32_e32 v13, v95
	v_exp_f32_e32 v14, v96
	v_exp_f32_e32 v15, v97
	v_max3_f32 v159, v159, v88, v89
	v_max3_f32 v250, v250, v90, v91
	v_max3_f32 v159, v159, v92, v93
	v_max3_f32 v250, v250, v94, v95
	v_max3_f32 v159, v159, v96, v97
	s_nop 1
	v_max3_f32 v159, v159, v66, v67
	v_max3_f32 v250, v250, v68, v69
	v_max3_f32 v159, v159, v70, v71
	v_max3_f32 v250, v250, v72, v73
	v_max3_f32 v159, v159, v74, v75
	v_max3_f32 v250, v250, v76, v77
	v_max3_f32 v159, v159, v78, v79
	v_max3_f32 v250, v250, v80, v81
	v_max_f32_e32 v0, v159, v250
	v_mov_b32_e32 v3, v0
	s_nop 1
	v_permlane32_swap_b32_e32 v0, v3
	v_max_f32_e32 v0, v0, v3
	s_nop 0
	v_cmp_lt_f32_e32 vcc, s30, v0
	s_cbranch_vccnz .Lat_r2

; DI int crow(int r, int hi) { return (r & 3) + 8 * (r >> 2) + 4 * hi; }
; DI void attn_tile(bool MASK, const LAS unsigned char* Ks, const LAS unsigned char* Vs, const bf16x8 (&qr)[6], f32x16& negm, float& mrun, float& lrun, f32x16& o0, f32x16& o1,
;                                        int kv0, int qrow, int r32, int hi) {
;     ...
;     if (MASK) {
;         asm volatile("" ::: "memory");
; #pragma unroll
;         for (int r = 0; r < 16; ++r) { const int kv = kv0 + crow(r, hi); if (kv > qrow) p0[r] = -INFINITY; if (kv + 32 > qrow) p1[r] = -INFINITY; }
;     }
.Lkf_skip2:
	s_waitcnt vmcnt(6)
	ds_write_b128 v209, v[142:145]
	ds_write_b128 v210, v[138:141]
	ds_write2_b64 v211, v[134:135], v[136:137] offset1:1
	s_ashr_i32 s35, s34, 31
	global_load_dwordx4 v[142:145], v[246:247], off
	global_load_dwordx4 v[138:141], v[248:249], off
	v_lshl_add_u64 v[246:247], s[34:35], 1, v[192:193]
	global_load_dwordx4 v[134:137], v[246:247], off
	s_branch .LBB0_848
.Lat_m2:
	s_waitcnt lgkmcnt(8)
	v_mfma_f32_32x32x16_bf16 v[66:81], v[226:229], v[154:157], v[50:65]
	s_waitcnt lgkmcnt(7)
	v_mfma_f32_32x32x16_bf16 v[66:81], v[230:233], v[150:153], v[66:81]
	s_waitcnt lgkmcnt(3)
	v_mfma_f32_32x32x16_bf16 v[66:81], v[234:237], v[146:149], v[66:81]
	s_waitcnt lgkmcnt(2)
	v_mfma_f32_32x32x16_bf16 v[66:81], v[238:241], v[126:129], v[66:81]
	s_waitcnt lgkmcnt(1)
	v_mfma_f32_32x32x16_bf16 v[66:81], v[242:245], v[122:125], v[66:81]
	s_waitcnt lgkmcnt(0)
	v_mfma_f32_32x32x16_bf16 v[66:81], v[246:249], v[118:121], v[66:81]
	s_setprio 0
	v_add_u32_e32 v3, v205, v208
	v_add_u32_e32 v0, 0xf000, v3
	v_add_u32_e32 v3, 0xe000, v3
	ds_read2_b64 v[214:217], v3 offset0:0 offset1:2
	ds_read2_b64 v[218:221], v0 offset0:32 offset1:34
	ds_read2_b64 v[222:225], v3 offset0:4 offset1:6
	ds_read2_b64 v[226:229], v0 offset0:36 offset1:38
	ds_read2_b64 v[230:233], v3 offset0:8 offset1:10
	ds_read2_b64 v[234:237], v0 offset0:40 offset1:42
	ds_read2_b64 v[238:241], v3 offset0:12 offset1:14
	ds_read2_b64 v[242:245], v0 offset0:44 offset1:46
	v_add_u32_e32 v0, s21, v207
	v_add_u32_e32 v4, 0xa0, v0
	v_add_u32_e32 v3, 0x80, v0
	v_cmp_le_i32_e32 vcc, v4, v49
	s_nop 5
	v_cndmask_b32_e32 v66, v212, v66, vcc
	v_cmp_lt_i32_e32 vcc, v3, v49
	s_nop 1
	v_cndmask_b32_e32 v83, v212, v83, vcc
	v_cmp_le_i32_e32 vcc, v3, v49
	v_add_u32_e32 v3, 0xa1, v0
	s_nop 0
	v_cndmask_b32_e32 v82, v212, v82, vcc
	v_cmp_le_i32_e32 vcc, v3, v49
	v_add_u32_e32 v3, 0x82, v0
	s_nop 0
	v_cndmask_b32_e32 v67, v212, v67, vcc
	v_cmp_le_i32_e32 vcc, v3, v49
	v_add_u32_e32 v3, 0xa2, v0
	s_nop 0
	v_cndmask_b32_e32 v84, v212, v84, vcc
	v_cmp_le_i32_e32 vcc, v3, v49
	v_add_u32_e32 v3, 0x83, v0
	s_nop 0
	v_cndmask_b32_e32 v68, v212, v68, vcc
	v_cmp_le_i32_e32 vcc, v3, v49
	v_add_u32_e32 v3, 0xa3, v0
	s_nop 0
	v_cndmask_b32_e32 v85, v212, v85, vcc
	v_cmp_le_i32_e32 vcc, v3, v49
	v_add_u32_e32 v3, 0x88, v0
	s_nop 0
	v_cndmask_b32_e32 v69, v212, v69, vcc
	v_cmp_le_i32_e32 vcc, v3, v49
	v_add_u32_e32 v3, 0xa8, v0
	s_nop 0
	v_cndmask_b32_e32 v86, v212, v86, vcc
	v_cmp_le_i32_e32 vcc, v3, v49
	v_add_u32_e32 v3, 0x89, v0
	s_nop 0
	v_cndmask_b32_e32 v70, v212, v70, vcc
	v_cmp_le_i32_e32 vcc, v3, v49
	v_add_u32_e32 v3, 0xa9, v0
	s_nop 0
	v_cndmask_b32_e32 v87, v212, v87, vcc
	v_cmp_le_i32_e32 vcc, v3, v49
	v_add_u32_e32 v3, 0x8a, v0
	s_nop 0
	v_cndmask_b32_e32 v71, v212, v71, vcc
	v_cmp_le_i32_e32 vcc, v3, v49
	v_add_u32_e32 v3, 0xaa, v0
	s_nop 0
	v_cndmask_b32_e32 v88, v212, v88, vcc
	v_cmp_le_i32_e32 vcc, v3, v49
	v_add_u32_e32 v3, 0x8b, v0
	s_nop 0
	v_cndmask_b32_e32 v72, v212, v72, vcc
	v_cmp_le_i32_e32 vcc, v3, v49
	v_add_u32_e32 v3, 0xab, v0
	s_nop 0
	v_cndmask_b32_e32 v89, v212, v89, vcc
	v_cmp_le_i32_e32 vcc, v3, v49
	v_add_u32_e32 v3, 0x90, v0
	s_nop 0
	v_cndmask_b32_e32 v73, v212, v73, vcc
	v_cmp_le_i32_e32 vcc, v3, v49
	v_add_u32_e32 v3, 0xb0, v0
	s_nop 0
	v_cndmask_b32_e32 v90, v212, v90, vcc
	v_cmp_le_i32_e32 vcc, v3, v49
	v_add_u32_e32 v3, 0x91, v0
	s_nop 0
	v_cndmask_b32_e32 v74, v212, v74, vcc
	v_cmp_le_i32_e32 vcc, v3, v49
	v_add_u32_e32 v3, 0xb1, v0
	s_nop 0
	v_cndmask_b32_e32 v91, v212, v91, vcc
	v_cmp_le_i32_e32 vcc, v3, v49
	v_add_u32_e32 v3, 0x92, v0
	s_nop 0
	v_cndmask_b32_e32 v75, v212, v75, vcc
	v_cmp_le_i32_e32 vcc, v3, v49
	v_add_u32_e32 v3, 0xb2, v0
	s_nop 0
	v_cndmask_b32_e32 v92, v212, v92, vcc
	v_cmp_le_i32_e32 vcc, v3, v49
	v_add_u32_e32 v3, 0x93, v0
	s_nop 0
	v_cndmask_b32_e32 v76, v212, v76, vcc
	v_cmp_le_i32_e32 vcc, v3, v49
	v_add_u32_e32 v3, 0xb3, v0
	s_nop 0
	v_cndmask_b32_e32 v93, v212, v93, vcc
	v_cmp_le_i32_e32 vcc, v3, v49
	v_add_u32_e32 v3, 0x98, v0
	s_nop 0
	v_cndmask_b32_e32 v77, v212, v77, vcc
	v_cmp_le_i32_e32 vcc, v3, v49
	v_add_u32_e32 v3, 0xb8, v0
	s_nop 0
	v_cndmask_b32_e32 v94, v212, v94, vcc
	v_cmp_le_i32_e32 vcc, v3, v49
	v_add_u32_e32 v3, 0x99, v0
	s_nop 0
	v_cndmask_b32_e32 v78, v212, v78, vcc
	v_cmp_le_i32_e32 vcc, v3, v49
	v_add_u32_e32 v3, 0xb9, v0
	s_nop 0
	v_cndmask_b32_e32 v95, v212, v95, vcc
	v_cmp_le_i32_e32 vcc, v3, v49
	v_add_u32_e32 v3, 0x9a, v0
	s_nop 0
	v_cndmask_b32_e32 v79, v212, v79, vcc
	v_cmp_le_i32_e32 vcc, v3, v49
	v_add_u32_e32 v3, 0xba, v0
	s_nop 0
	v_cndmask_b32_e32 v96, v212, v96, vcc
	v_cmp_le_i32_e32 vcc, v3, v49
	v_add_u32_e32 v3, 0x9b, v0
	v_add_u32_e32 v0, 0xbb, v0
	v_cndmask_b32_e32 v80, v212, v80, vcc
	v_cmp_le_i32_e32 vcc, v3, v49
	s_nop 1
	v_cndmask_b32_e32 v97, v212, v97, vcc
	v_cmp_le_i32_e32 vcc, v0, v49
	s_nop 1
	v_cndmask_b32_e32 v81, v212, v81, vcc
